# grid barrier: all workgroups poll the cross-XCD arrival counter directly against (round+1)*nx; TOPGEN and per-XCD XGEN release hops removed
# speedup vs baseline: 1.0021x; 1.0021x over previous
.LBB0_440:
	v_readlane_b32 s6, v254, 40
	v_readlane_b32 s7, v254, 41
	v_readlane_b32 s12, v254, 44
	v_readlane_b32 s13, v254, 45
	v_mov_b32_e32 v3, 1
	v_cvt_f32_u32_e32 v4, v2
	v_sub_u32_e32 v6, 0, v2
	s_nop 1
	global_atomic_add v5, v129, v3, s[6:7] sc0
	v_rcp_iflag_f32_e32 v4, v4
	s_waitcnt lgkmcnt(0)
	v_readfirstlane_b32 s14, v2
	v_readfirstlane_b32 s15, v0
	v_mul_f32_e32 v4, 0x4f7ffffe, v4
	v_cvt_u32_f32_e32 v4, v4
	v_mul_lo_u32 v1, v6, v4
	v_mul_hi_u32 v1, v4, v1
	v_add_u32_e32 v1, v4, v1
	s_waitcnt vmcnt(0)
	v_mul_hi_u32 v1, v5, v1
	v_mul_lo_u32 v6, v1, v2
	v_sub_u32_e32 v6, v5, v6
	v_add_u32_e32 v4, 1, v1
	v_cmp_ge_u32_e32 vcc, v6, v2
	s_nop 1
	v_cndmask_b32_e32 v1, v1, v4, vcc
	v_sub_u32_e32 v4, v6, v2
	v_cndmask_b32_e32 v6, v6, v4, vcc
	v_add_u32_e32 v4, 1, v1
	v_cmp_ge_u32_e32 vcc, v6, v2
	s_nop 1
	v_cndmask_b32_e32 v1, v1, v4, vcc
	v_readfirstlane_b32 s16, v1
	v_readfirstlane_b32 s17, v5
	s_add_i32 s19, s16, 1
	s_mul_i32 s20, s19, s14
	s_add_i32 s17, s17, 1
	s_mul_i32 s19, s19, s15
	s_cmp_lg_u32 s17, s20
	s_cbranch_scc1 .Lxb_poll
	buffer_wbl2 sc1
	s_waitcnt vmcnt(0)
	global_atomic_add v129, v3, s[12:13]
.Lxb_poll:
	s_mov_b32 s21, 0
.Lxb_spin:
	global_load_dword v4, v129, s[12:13] sc1
	s_waitcnt vmcnt(0)
	v_readfirstlane_b32 s20, v4
	s_sub_i32 s20, s20, s19
	s_cmp_ge_i32 s20, 0
	s_cbranch_scc1 .Lxb_done
	s_add_i32 s21, s21, 1
	s_cmp_lt_u32 s21, 0x2000
	s_cbranch_scc1 .Lxb_spin
.Lxb_done:
	buffer_inv sc1
	s_waitcnt vmcnt(0)
